# GLA o^T stores widened to dwordx4 with v_permlane32_swap (2 stores per wave-chunk instead of 4); on top of A2 r-tile rewrite
# baseline (speedup 1.0000x reference)
; __device__ __forceinline__ unsigned cvtpk(float lo, float hi) { f32x2 v = {lo, hi}; bf16x2_t b = __builtin_convertvector(v, bf16x2_t); return __builtin_bit_cast(unsigned, b); }
; __device__ __forceinline__ void gla_phase(LAS unsigned char* lds, const bf16* Q, const bf16* K, const bf16* V, const bf16* Z, bf16* OF, bf16* OB,
;                                           const float* wgf, const float* bgf, const float* wgb, const float* bgb, const int wave_s) {
;     ...
;             { const size_t row = (size_t)gla_row(n, 32 * wi + r, b, dir); bf16* op = O + row * 1024 + hh * 256 + vh * 128 + 32 * wv + 4 * h;
; #pragma unroll
;               for (int g4 = 0; g4 < 4; ++g4) { v2u w2; w2.x = cvtpk(oT[4 * g4], oT[4 * g4 + 1]); w2.y = cvtpk(oT[4 * g4 + 2], oT[4 * g4 + 3]); *(v2u*)(op + 8 * g4) = w2; } }
.LBB0_264:
	s_add_i32 s0, s96, 0xffffff00
	s_cmp_lt_u32 s95, 4
	s_cselect_b32 s0, s96, s0
	v_add_u32_e32 v80, s0, v155
	s_cselect_b32 s0, 0xff, s94
	v_sub_u32_e32 v81, s0, v80
	v_cndmask_b32_e64 v80, v81, v80, s[82:83]
	s_cselect_b32 s0, s93, s97
	v_add_u32_e32 v80, s0, v80
	v_ashrrev_i32_e32 v81, 31, v80
	v_lshlrev_b64 v[80:81], 11, v[80:81]
	v_lshl_add_u64 v[80:81], v[148:149], 0, v[80:81]
	v_cvt_pk_bf16_f32 v64, v64, v65
	v_cvt_pk_bf16_f32 v65, v66, v67
	v_cvt_pk_bf16_f32 v66, v68, v69
	v_cvt_pk_bf16_f32 v67, v70, v71
	v_cvt_pk_bf16_f32 v68, v72, v73
	v_cvt_pk_bf16_f32 v69, v74, v75
	v_cvt_pk_bf16_f32 v70, v76, v77
	v_cvt_pk_bf16_f32 v71, v78, v79
	v_mbcnt_lo_u32_b32 v82, -1, 0
	v_mbcnt_hi_u32_b32 v82, -1, v82
	v_and_b32_e32 v82, 32, v82
	v_lshrrev_b32_e32 v82, 2, v82
	v_add_co_u32_e32 v80, vcc, v80, v82
	s_nop 1
	v_addc_co_u32_e32 v81, vcc, 0, v81, vcc
	v_permlane32_swap_b32_e32 v64, v66
	v_permlane32_swap_b32_e32 v65, v67
	v_permlane32_swap_b32_e32 v68, v70
	v_permlane32_swap_b32_e32 v69, v71
	global_store_dwordx4 v[80:81], v[64:67], off
	global_store_dwordx4 v[80:81], v[68:71], off offset:32
	s_add_i32 s96, s96, 64
	s_add_i32 s95, s95, 1
	s_cmpk_eq_i32 s96, 0x1100
	v_subrev_u32_e32 v206, 64, v206
	s_cbranch_scc1 .LBB0_255

; __device__ __forceinline__ void gla_phase(LAS unsigned char* lds, const bf16* Q, const bf16* K, const bf16* V, const bf16* Z, bf16* OF, bf16* OB,
;                                           const float* wgf, const float* bgf, const float* wgb, const float* bgb, const int wave_s) {
;     ...
;             for (int i = 0; i < 2; ++i) { const int idx = tid + 512 * i, p = idx >> 4, c8 = idx & 15; const int pcol = ((((p >> 3) ^ (c8 & 7)) << 4) + ((p & 7) << 1));
;                 const f32x4 b0 = *(const LAS f32x4*)(Bc + p * 132 + 8 * c8), b1 = *(const LAS f32x4*)(Bc + p * 132 + 8 * c8 + 4);
;                 const f32x4 t00 = *(const LAS f32x4*)(Seg + 8 * c8), t01 = *(const LAS f32x4*)(Seg + 8 * c8 + 4), t10 = *(const LAS f32x4*)(Seg + 128 + 8 * c8), t11 = *(const LAS f32x4*)(Seg + 128 + 8 * c8 + 4);
;                 float qf[8], kf[8], bc[8], dc[8];
;                 qf[0] = bflo(rq[i].x); qf[1] = bfhi(rq[i].x); qf[2] = bflo(rq[i].y); qf[3] = bfhi(rq[i].y); qf[4] = bflo(rq[i].z); qf[5] = bfhi(rq[i].z); qf[6] = bflo(rq[i].w); qf[7] = bfhi(rq[i].w);
;                 kf[0] = bflo(rk[i].x); kf[1] = bfhi(rk[i].x); kf[2] = bflo(rk[i].y); kf[3] = bfhi(rk[i].y); kf[4] = bflo(rk[i].z); kf[5] = bfhi(rk[i].z); kf[6] = bflo(rk[i].w); kf[7] = bfhi(rk[i].w);
; #pragma unroll
;                 for (int e = 0; e < 4; ++e) { bc[e] = b0[e] + (p >= 32 ? t00[e] : 0.f); bc[4 + e] = b1[e] + (p >= 32 ? t01[e] : 0.f); dc[e] = __expf(t00[e] + t10[e]); dc[4 + e] = __expf(t01[e] + t11[e]); }
;                 if (p == 0) { *(LAS f32x4*)(Dec + 8 * c8) = (f32x4){dc[0], dc[1], dc[2], dc[3]}; *(LAS f32x4*)(Dec + 8 * c8 + 4) = (f32x4){dc[4], dc[5], dc[6], dc[7]}; }
;                 float qe[8], ke[8], kn[8];
; #pragma unroll
;                 for (int e = 0; e < 8; ++e) { const float ex = __expf(bc[e]); const float inv = __builtin_amdgcn_rcpf(ex); qe[e] = qf[e] * ex; ke[e] = kf[e] * inv; kn[e] = ke[e] * dc[e]; }
;                 v4u wq, wk; wq.x = cvtpk(qe[0], qe[1]); wq.y = cvtpk(qe[2], qe[3]); wq.z = cvtpk(qe[4], qe[5]); wq.w = cvtpk(qe[6], qe[7]);
;                 wk.x = cvtpk(ke[0], ke[1]); wk.y = cvtpk(ke[2], ke[3]); wk.z = cvtpk(ke[4], ke[5]); wk.w = cvtpk(ke[6], ke[7]);
;                 *(LAS v4u*)(Qe + p * 272 + 16 * c8) = wq; *(LAS v4u*)(Ke + p * 272 + 16 * c8) = wk;
; #pragma unroll
;                 for (int e = 0; e < 8; e += 2) { const unsigned pk = cvtpk(kn[e], kn[e + 1]);
.LBB0_267:
	s_or_b64 exec, exec, s[0:1]
	v_cndmask_b32_e64 v80, 0, v80, s[8:9]
	v_cndmask_b32_e64 v72, 0, v72, s[8:9]
	s_waitcnt lgkmcnt(1)
	v_add_f32_e32 v80, v84, v80
	s_waitcnt lgkmcnt(0)
	v_add_f32_e32 v84, v76, v72
	v_cndmask_b32_e64 v72, 0, v81, s[8:9]
	v_add_f32_e32 v76, v85, v72
	v_cndmask_b32_e64 v72, 0, v73, s[8:9]
	v_add_f32_e32 v81, v77, v72
	v_cndmask_b32_e64 v72, 0, v82, s[8:9]
	v_add_f32_e32 v77, v86, v72
	v_cndmask_b32_e64 v72, 0, v74, s[8:9]
	v_add_f32_e32 v86, v78, v72
	v_cndmask_b32_e64 v72, 0, v83, s[8:9]
	v_add_f32_e32 v78, v87, v72
	v_mul_f32_e32 v72, 0x3fb8aa3b, v80
	v_mul_f32_e32 v73, 0x3fb8aa3b, v76
	v_exp_f32_e32 v72, v72
	v_exp_f32_e32 v73, v73
	v_cndmask_b32_e64 v74, 0, v75, s[8:9]
	v_add_f32_e32 v87, v79, v74
	v_rcp_f32_e32 v74, v72
	v_rcp_f32_e32 v75, v73
	v_mul_f32_e32 v76, 0x3fb8aa3b, v77
	v_mul_f32_e32 v77, 0x3fb8aa3b, v78
	v_exp_f32_e32 v76, v76
	v_exp_f32_e32 v77, v77
	s_waitcnt vmcnt(2)
	v_lshlrev_b32_e32 v208, 16, v100
	v_and_b32_e32 v209, 0xffff0000, v100
	v_pk_mul_f32 v[74:75], v[74:75], v[208:209]
	v_lshlrev_b32_e32 v210, 16, v101
	v_pk_mul_f32 v[78:79], v[68:69], v[74:75]
	v_rcp_f32_e32 v68, v76
	v_rcp_f32_e32 v69, v77
	v_and_b32_e32 v211, 0xffff0000, v101
	v_mul_f32_e32 v80, 0x3fb8aa3b, v84
	v_exp_f32_e32 v80, v80
	v_pk_mul_f32 v[82:83], v[68:69], v[210:211]
	v_mul_f32_e32 v69, 0x3fb8aa3b, v81
	v_exp_f32_e32 v81, v69
	v_mul_f32_e32 v69, 0x3fb8aa3b, v86
	v_pk_mul_f32 v[84:85], v[70:71], v[82:83]
	v_exp_f32_e32 v70, v69
	v_mul_f32_e32 v69, 0x3fb8aa3b, v87
	v_exp_f32_e32 v71, v69
	v_rcp_f32_e32 v68, v80
	v_rcp_f32_e32 v69, v81
	v_rcp_f32_e32 v86, v70
	v_rcp_f32_e32 v87, v71
	v_lshlrev_b32_e32 v88, 16, v96
	v_and_b32_e32 v89, 0xffff0000, v96
	v_lshlrev_b32_e32 v90, 16, v97
	v_and_b32_e32 v91, 0xffff0000, v97
	v_lshlrev_b32_e32 v92, 16, v98
	v_and_b32_e32 v93, 0xffff0000, v98
	v_lshlrev_b32_e32 v94, 16, v99
	v_and_b32_e32 v95, 0xffff0000, v99
	v_lshlrev_b32_e32 v212, 16, v102
	v_and_b32_e32 v213, 0xffff0000, v102
	v_lshlrev_b32_e32 v214, 16, v103
	v_and_b32_e32 v215, 0xffff0000, v103
	v_pk_mul_f32 v[72:73], v[72:73], v[88:89]
	v_pk_mul_f32 v[76:77], v[76:77], v[90:91]
	v_pk_mul_f32 v[80:81], v[80:81], v[92:93]
	v_pk_mul_f32 v[88:89], v[68:69], v[212:213]
	v_pk_mul_f32 v[68:69], v[70:71], v[94:95]
	v_pk_mul_f32 v[86:87], v[86:87], v[214:215]
	v_pk_mul_f32 v[90:91], v[64:65], v[88:89]
	v_pk_mul_f32 v[92:93], v[66:67], v[86:87]
	v_cvt_pk_bf16_f32 v64, v72, v73
	v_cvt_pk_bf16_f32 v65, v76, v77
	v_cvt_pk_bf16_f32 v66, v80, v81
	v_cvt_pk_bf16_f32 v67, v68, v69
	v_cvt_pk_bf16_f32 v68, v74, v75
	v_cvt_pk_bf16_f32 v69, v82, v83
	v_cvt_pk_bf16_f32 v70, v88, v89
	v_cvt_pk_bf16_f32 v71, v86, v87
	ds_write_b128 v175, v[64:67]
	ds_write_b128 v175, v[68:71] offset:17408
	v_cvt_pk_bf16_f32 v64, v78, v79
	ds_write_b16 v176, v64 offset:34816
	ds_write_b16_d16_hi v176, v64 offset:34960
	v_cvt_pk_bf16_f32 v64, v84, v85
	ds_write_b16 v176, v64 offset:35104
	ds_write_b16_d16_hi v176, v64 offset:35248
	v_cvt_pk_bf16_f32 v64, v90, v91
	ds_write_b16 v176, v64 offset:35392
	ds_write_b16_d16_hi v176, v64 offset:35536
	v_cvt_pk_bf16_f32 v64, v92, v93
	ds_write_b16 v176, v64 offset:35680
	ds_write_b16_d16_hi v176, v64 offset:35824
	s_waitcnt vmcnt(2)
	ds_write_b16 v176, v104 offset:53248
	ds_write_b16_d16_hi v176, v104 offset:53392
	ds_write_b16 v176, v105 offset:53536
	ds_write_b16_d16_hi v176, v105 offset:53680
	ds_write_b16 v176, v106 offset:53824
	ds_write_b16_d16_hi v176, v106 offset:53968
	ds_write_b16 v176, v107 offset:54112
	ds_write_b16_d16_hi v176, v107 offset:54256
	ds_read_b128 v[64:67], v160
	ds_read_b128 v[80:83], v159
	ds_read_b128 v[72:75], v159 offset:16
	ds_read_b128 v[88:91], v160 offset:16
	ds_read_b128 v[84:87], v177
	ds_read_b128 v[76:79], v177 offset:16
	s_waitcnt lgkmcnt(4)
	v_add_f32_e32 v64, v80, v64
	v_add_f32_e32 v65, v81, v65
	v_add_f32_e32 v66, v82, v66
	v_add_f32_e32 v67, v83, v67
	v_mul_f32_e32 v64, 0x3fb8aa3b, v64
	v_mul_f32_e32 v65, 0x3fb8aa3b, v65
	v_mul_f32_e32 v66, 0x3fb8aa3b, v66
	v_mul_f32_e32 v67, 0x3fb8aa3b, v67
	v_exp_f32_e32 v68, v64
	s_waitcnt lgkmcnt(2)
	v_add_f32_e32 v64, v72, v88
	v_exp_f32_e32 v69, v65
	v_add_f32_e32 v65, v73, v89
	v_exp_f32_e32 v70, v66
	v_add_f32_e32 v66, v74, v90
	v_exp_f32_e32 v71, v67
	v_add_f32_e32 v67, v75, v91
	v_mul_f32_e32 v64, 0x3fb8aa3b, v64
	v_mul_f32_e32 v65, 0x3fb8aa3b, v65
	v_mul_f32_e32 v66, 0x3fb8aa3b, v66
	v_mul_f32_e32 v67, 0x3fb8aa3b, v67
	v_exp_f32_e32 v64, v64
	v_exp_f32_e32 v65, v65
	v_exp_f32_e32 v66, v66
	v_exp_f32_e32 v67, v67
	s_and_saveexec_b64 s[0:1], s[14:15]
	s_cbranch_execz .LBB0_269
	ds_write_b128 v161, v[68:71]
	ds_write_b128 v161, v[64:67] offset:16
; __device__ __forceinline__ void gla_phase(LAS unsigned char* lds, const bf16* Q, const bf16* K, const bf16* V, const bf16* Z, bf16* OF, bf16* OB,
;                                           const float* wgf, const float* bgf, const float* wgb, const float* bgb, const int wave_s) {
;     ...
;             for (int i = 0; i < 2; ++i) { const int idx = tid + 512 * i, p = idx >> 4, c8 = idx & 15; const int pcol = ((((p >> 3) ^ (c8 & 7)) << 4) + ((p & 7) << 1));
;                 const f32x4 b0 = *(const LAS f32x4*)(Bc + p * 132 + 8 * c8), b1 = *(const LAS f32x4*)(Bc + p * 132 + 8 * c8 + 4);
;                 const f32x4 t00 = *(const LAS f32x4*)(Seg + 8 * c8), t01 = *(const LAS f32x4*)(Seg + 8 * c8 + 4), t10 = *(const LAS f32x4*)(Seg + 128 + 8 * c8), t11 = *(const LAS f32x4*)(Seg + 128 + 8 * c8 + 4);
;                 float qf[8], kf[8], bc[8], dc[8];
;                 qf[0] = bflo(rq[i].x); qf[1] = bfhi(rq[i].x); qf[2] = bflo(rq[i].y); qf[3] = bfhi(rq[i].y); qf[4] = bflo(rq[i].z); qf[5] = bfhi(rq[i].z); qf[6] = bflo(rq[i].w); qf[7] = bfhi(rq[i].w);
;                 kf[0] = bflo(rk[i].x); kf[1] = bfhi(rk[i].x); kf[2] = bflo(rk[i].y); kf[3] = bfhi(rk[i].y); kf[4] = bflo(rk[i].z); kf[5] = bfhi(rk[i].z); kf[6] = bflo(rk[i].w); kf[7] = bfhi(rk[i].w);
; #pragma unroll
;                 for (int e = 0; e < 4; ++e) { bc[e] = b0[e] + (p >= 32 ? t00[e] : 0.f); bc[4 + e] = b1[e] + (p >= 32 ? t01[e] : 0.f); dc[e] = __expf(t00[e] + t10[e]); dc[4 + e] = __expf(t01[e] + t11[e]); }
;                 if (p == 0) { *(LAS f32x4*)(Dec + 8 * c8) = (f32x4){dc[0], dc[1], dc[2], dc[3]}; *(LAS f32x4*)(Dec + 8 * c8 + 4) = (f32x4){dc[4], dc[5], dc[6], dc[7]}; }
;                 float qe[8], ke[8], kn[8];
; #pragma unroll
;                 for (int e = 0; e < 8; ++e) { const float ex = __expf(bc[e]); const float inv = __builtin_amdgcn_rcpf(ex); qe[e] = qf[e] * ex; ke[e] = kf[e] * inv; kn[e] = ke[e] * dc[e]; }
;                 v4u wq, wk; wq.x = cvtpk(qe[0], qe[1]); wq.y = cvtpk(qe[2], qe[3]); wq.z = cvtpk(qe[4], qe[5]); wq.w = cvtpk(qe[6], qe[7]);
;                 wk.x = cvtpk(ke[0], ke[1]); wk.y = cvtpk(ke[2], ke[3]); wk.z = cvtpk(ke[4], ke[5]); wk.w = cvtpk(ke[6], ke[7]);
;                 *(LAS v4u*)(Qe + p * 272 + 16 * c8) = wq; *(LAS v4u*)(Ke + p * 272 + 16 * c8) = wk;
; #pragma unroll
;                 for (int e = 0; e < 8; e += 2) { const unsigned pk = cvtpk(kn[e], kn[e + 1]);
.LBB0_269:
	s_or_b64 exec, exec, s[0:1]
	v_cndmask_b32_e64 v80, 0, v80, s[12:13]
	v_cndmask_b32_e64 v72, 0, v72, s[12:13]
	s_waitcnt lgkmcnt(1)
	v_add_f32_e32 v80, v84, v80
	s_waitcnt lgkmcnt(0)
	v_add_f32_e32 v84, v76, v72
	v_cndmask_b32_e64 v72, 0, v81, s[12:13]
	v_add_f32_e32 v76, v85, v72
	v_cndmask_b32_e64 v72, 0, v73, s[12:13]
	v_add_f32_e32 v81, v77, v72
	v_cndmask_b32_e64 v72, 0, v82, s[12:13]
	v_add_f32_e32 v77, v86, v72
	v_cndmask_b32_e64 v72, 0, v74, s[12:13]
	v_add_f32_e32 v86, v78, v72
	v_cndmask_b32_e64 v72, 0, v83, s[12:13]
	v_add_f32_e32 v78, v87, v72
	v_mul_f32_e32 v72, 0x3fb8aa3b, v80
	v_mul_f32_e32 v73, 0x3fb8aa3b, v76
	v_exp_f32_e32 v72, v72
	v_exp_f32_e32 v73, v73
	v_cndmask_b32_e64 v74, 0, v75, s[12:13]
	v_add_f32_e32 v87, v79, v74
	v_rcp_f32_e32 v74, v72
	v_rcp_f32_e32 v75, v73
	v_mul_f32_e32 v76, 0x3fb8aa3b, v77
	v_mul_f32_e32 v77, 0x3fb8aa3b, v78
	v_exp_f32_e32 v76, v76
	v_exp_f32_e32 v77, v77
	s_waitcnt vmcnt(2)
	v_lshlrev_b32_e32 v208, 16, v112
	v_and_b32_e32 v209, 0xffff0000, v112
	v_pk_mul_f32 v[74:75], v[74:75], v[208:209]
	v_lshlrev_b32_e32 v210, 16, v113
	v_pk_mul_f32 v[78:79], v[68:69], v[74:75]
	v_rcp_f32_e32 v68, v76
	v_rcp_f32_e32 v69, v77
	v_and_b32_e32 v211, 0xffff0000, v113
	v_mul_f32_e32 v80, 0x3fb8aa3b, v84
	v_exp_f32_e32 v80, v80
	v_pk_mul_f32 v[82:83], v[68:69], v[210:211]
	v_mul_f32_e32 v69, 0x3fb8aa3b, v81
	v_exp_f32_e32 v81, v69
	v_mul_f32_e32 v69, 0x3fb8aa3b, v86
	v_pk_mul_f32 v[84:85], v[70:71], v[82:83]
	v_exp_f32_e32 v70, v69
	v_mul_f32_e32 v69, 0x3fb8aa3b, v87
	v_exp_f32_e32 v71, v69
	v_rcp_f32_e32 v68, v80
	v_rcp_f32_e32 v69, v81
	v_rcp_f32_e32 v86, v70
	v_rcp_f32_e32 v87, v71
	v_lshlrev_b32_e32 v88, 16, v108
	v_and_b32_e32 v89, 0xffff0000, v108
	v_lshlrev_b32_e32 v90, 16, v109
	v_and_b32_e32 v91, 0xffff0000, v109
	v_lshlrev_b32_e32 v92, 16, v110
	v_and_b32_e32 v93, 0xffff0000, v110
	v_lshlrev_b32_e32 v94, 16, v111
	v_and_b32_e32 v95, 0xffff0000, v111
	v_lshlrev_b32_e32 v212, 16, v114
	v_and_b32_e32 v213, 0xffff0000, v114
	v_lshlrev_b32_e32 v214, 16, v115
	v_and_b32_e32 v215, 0xffff0000, v115
	v_pk_mul_f32 v[72:73], v[72:73], v[88:89]
	v_pk_mul_f32 v[76:77], v[76:77], v[90:91]
	v_pk_mul_f32 v[80:81], v[80:81], v[92:93]
	v_pk_mul_f32 v[88:89], v[68:69], v[212:213]
	v_pk_mul_f32 v[68:69], v[70:71], v[94:95]
	v_pk_mul_f32 v[86:87], v[86:87], v[214:215]
	v_pk_mul_f32 v[90:91], v[64:65], v[88:89]
	v_pk_mul_f32 v[92:93], v[66:67], v[86:87]
	v_cvt_pk_bf16_f32 v64, v72, v73
	v_cvt_pk_bf16_f32 v65, v76, v77
	v_cvt_pk_bf16_f32 v66, v80, v81
	v_cvt_pk_bf16_f32 v67, v68, v69
	v_cvt_pk_bf16_f32 v68, v74, v75
	v_cvt_pk_bf16_f32 v69, v82, v83
	v_cvt_pk_bf16_f32 v70, v88, v89
	v_cvt_pk_bf16_f32 v71, v86, v87
	ds_write_b128 v178, v[64:67]
	ds_write_b128 v178, v[68:71] offset:17408
	v_cvt_pk_bf16_f32 v64, v78, v79
	ds_write_b16 v179, v64 offset:34816
	ds_write_b16_d16_hi v179, v64 offset:34960
	v_cvt_pk_bf16_f32 v64, v84, v85
	ds_write_b16 v179, v64 offset:35104
	ds_write_b16_d16_hi v179, v64 offset:35248
	v_cvt_pk_bf16_f32 v64, v90, v91
	ds_write_b16 v179, v64 offset:35392
	ds_write_b16_d16_hi v179, v64 offset:35536
	v_cvt_pk_bf16_f32 v64, v92, v93
	ds_write_b16 v179, v64 offset:35680
	ds_write_b16_d16_hi v179, v64 offset:35824
	s_waitcnt vmcnt(2)
	ds_write_b16 v179, v116 offset:53248
	ds_write_b16_d16_hi v179, v116 offset:53392
	ds_write_b16 v179, v117 offset:53536
	ds_write_b16_d16_hi v179, v117 offset:53680
	ds_write_b16 v179, v118 offset:53824
	ds_write_b16_d16_hi v179, v118 offset:53968
	ds_write_b16 v179, v119 offset:54112
	ds_write_b16_d16_hi v179, v119 offset:54256
	s_and_saveexec_b64 s[0:1], s[4:5]
	ds_write_b128 v201, v[120:123]
	s_or_b64 exec, exec, s[0:1]
	s_cmpk_lt_u32 s95, 0x42
	s_cselect_b64 s[0:1], -1, 0
	s_and_b64 s[50:51], s[4:5], s[0:1]
	s_and_saveexec_b64 s[0:1], s[50:51]
	s_cbranch_execz .LBB0_273
	s_cmp_lt_u32 s95, 2
	s_movk_i32 s50, 0xff80
	s_cselect_b32 s50, 0x80, s50
	s_cselect_b32 s51, 0xff, s94
	s_cselect_b32 s84, s93, s97
	s_add_i32 s85, s96, s50
	s_sub_i32 s50, s51, s50
	v_add_u32_e32 v64, s85, v151
	v_add_u32_e32 v65, s50, v206
	v_cndmask_b32_e64 v64, v65, v64, s[82:83]
	v_add_u32_e32 v64, s84, v64
	v_ashrrev_i32_e32 v65, 31, v64
	v_lshlrev_b64 v[64:65], 6, v[64:65]
	v_lshl_add_u64 v[64:65], v[146:147], 0, v[64:65]
	global_load_dwordx4 v[120:123], v[64:65], off

; __device__ __forceinline__ unsigned cvtpk(float lo, float hi) { f32x2 v = {lo, hi}; bf16x2_t b = __builtin_convertvector(v, bf16x2_t); return __builtin_bit_cast(unsigned, b); }
; __device__ __forceinline__ void gla_phase(LAS unsigned char* lds, const bf16* Q, const bf16* K, const bf16* V, const bf16* Z, bf16* OF, bf16* OB,
;                                           const float* wgf, const float* bgf, const float* wgb, const float* bgb, const int wave_s) {
;     ...
;             { const size_t row = (size_t)gla_row(n, 32 * wi + r, b, dir); bf16* op = O + row * 1024 + hh * 256 + vh * 128 + 32 * wv + 4 * h;
; #pragma unroll
;               for (int g4 = 0; g4 < 4; ++g4) { v2u w2; w2.x = cvtpk(oT[4 * g4], oT[4 * g4 + 1]); w2.y = cvtpk(oT[4 * g4 + 2], oT[4 * g4 + 3]); *(v2u*)(op + 8 * g4) = w2; } }
.LBB0_1042:
	s_add_i32 s10, s96, 0xffffff00
	s_cmp_lt_u32 s7, 4
	s_cselect_b32 s10, s96, s10
	v_add_u32_e32 v80, s10, v155
	s_cselect_b32 s10, 0xff, s6
	v_sub_u32_e32 v81, s10, v80
	v_cndmask_b32_e64 v80, v81, v80, s[92:93]
	s_cselect_b32 s10, s5, s97
	v_add_u32_e32 v80, s10, v80
	v_ashrrev_i32_e32 v81, 31, v80
	v_lshlrev_b64 v[80:81], 11, v[80:81]
	v_lshl_add_u64 v[80:81], v[148:149], 0, v[80:81]
	v_cvt_pk_bf16_f32 v64, v64, v65
	v_cvt_pk_bf16_f32 v65, v66, v67
	v_cvt_pk_bf16_f32 v66, v68, v69
	v_cvt_pk_bf16_f32 v67, v70, v71
	v_cvt_pk_bf16_f32 v68, v72, v73
	v_cvt_pk_bf16_f32 v69, v74, v75
	v_cvt_pk_bf16_f32 v70, v76, v77
	v_cvt_pk_bf16_f32 v71, v78, v79
	v_mbcnt_lo_u32_b32 v82, -1, 0
	v_mbcnt_hi_u32_b32 v82, -1, v82
	v_and_b32_e32 v82, 32, v82
	v_lshrrev_b32_e32 v82, 2, v82
	v_add_co_u32_e32 v80, vcc, v80, v82
	s_nop 1
	v_addc_co_u32_e32 v81, vcc, 0, v81, vcc
	v_permlane32_swap_b32_e32 v64, v66
	v_permlane32_swap_b32_e32 v65, v67
	v_permlane32_swap_b32_e32 v68, v70
	v_permlane32_swap_b32_e32 v69, v71
	global_store_dwordx4 v[80:81], v[64:67], off
	global_store_dwordx4 v[80:81], v[68:71], off offset:32
	s_add_i32 s96, s96, 64
	s_add_i32 s7, s7, 1
	s_cmpk_eq_i32 s96, 0x1100
	v_subrev_u32_e32 v206, 64, v206
	s_cbranch_scc1 .LBB0_1033

; __device__ __forceinline__ void gla_phase(LAS unsigned char* lds, const bf16* Q, const bf16* K, const bf16* V, const bf16* Z, bf16* OF, bf16* OB,
;                                           const float* wgf, const float* bgf, const float* wgb, const float* bgb, const int wave_s) {
;     ...
;             for (int i = 0; i < 2; ++i) { const int idx = tid + 512 * i, p = idx >> 4, c8 = idx & 15; const int pcol = ((((p >> 3) ^ (c8 & 7)) << 4) + ((p & 7) << 1));
;                 const f32x4 b0 = *(const LAS f32x4*)(Bc + p * 132 + 8 * c8), b1 = *(const LAS f32x4*)(Bc + p * 132 + 8 * c8 + 4);
;                 const f32x4 t00 = *(const LAS f32x4*)(Seg + 8 * c8), t01 = *(const LAS f32x4*)(Seg + 8 * c8 + 4), t10 = *(const LAS f32x4*)(Seg + 128 + 8 * c8), t11 = *(const LAS f32x4*)(Seg + 128 + 8 * c8 + 4);
;                 float qf[8], kf[8], bc[8], dc[8];
;                 qf[0] = bflo(rq[i].x); qf[1] = bfhi(rq[i].x); qf[2] = bflo(rq[i].y); qf[3] = bfhi(rq[i].y); qf[4] = bflo(rq[i].z); qf[5] = bfhi(rq[i].z); qf[6] = bflo(rq[i].w); qf[7] = bfhi(rq[i].w);
;                 kf[0] = bflo(rk[i].x); kf[1] = bfhi(rk[i].x); kf[2] = bflo(rk[i].y); kf[3] = bfhi(rk[i].y); kf[4] = bflo(rk[i].z); kf[5] = bfhi(rk[i].z); kf[6] = bflo(rk[i].w); kf[7] = bfhi(rk[i].w);
; #pragma unroll
;                 for (int e = 0; e < 4; ++e) { bc[e] = b0[e] + (p >= 32 ? t00[e] : 0.f); bc[4 + e] = b1[e] + (p >= 32 ? t01[e] : 0.f); dc[e] = __expf(t00[e] + t10[e]); dc[4 + e] = __expf(t01[e] + t11[e]); }
;                 if (p == 0) { *(LAS f32x4*)(Dec + 8 * c8) = (f32x4){dc[0], dc[1], dc[2], dc[3]}; *(LAS f32x4*)(Dec + 8 * c8 + 4) = (f32x4){dc[4], dc[5], dc[6], dc[7]}; }
;                 float qe[8], ke[8], kn[8];
; #pragma unroll
;                 for (int e = 0; e < 8; ++e) { const float ex = __expf(bc[e]); const float inv = __builtin_amdgcn_rcpf(ex); qe[e] = qf[e] * ex; ke[e] = kf[e] * inv; kn[e] = ke[e] * dc[e]; }
;                 v4u wq, wk; wq.x = cvtpk(qe[0], qe[1]); wq.y = cvtpk(qe[2], qe[3]); wq.z = cvtpk(qe[4], qe[5]); wq.w = cvtpk(qe[6], qe[7]);
;                 wk.x = cvtpk(ke[0], ke[1]); wk.y = cvtpk(ke[2], ke[3]); wk.z = cvtpk(ke[4], ke[5]); wk.w = cvtpk(ke[6], ke[7]);
;                 *(LAS v4u*)(Qe + p * 272 + 16 * c8) = wq; *(LAS v4u*)(Ke + p * 272 + 16 * c8) = wk;
; #pragma unroll
;                 for (int e = 0; e < 8; e += 2) { const unsigned pk = cvtpk(kn[e], kn[e + 1]);
.LBB0_1045:
	s_or_b64 exec, exec, s[10:11]
	v_cndmask_b32_e64 v80, 0, v80, s[18:19]
	v_cndmask_b32_e64 v72, 0, v72, s[18:19]
	s_waitcnt lgkmcnt(1)
	v_add_f32_e32 v80, v84, v80
	s_waitcnt lgkmcnt(0)
	v_add_f32_e32 v84, v76, v72
	v_cndmask_b32_e64 v72, 0, v81, s[18:19]
	v_add_f32_e32 v76, v85, v72
	v_cndmask_b32_e64 v72, 0, v73, s[18:19]
	v_add_f32_e32 v81, v77, v72
	v_cndmask_b32_e64 v72, 0, v82, s[18:19]
	v_add_f32_e32 v77, v86, v72
	v_cndmask_b32_e64 v72, 0, v74, s[18:19]
	v_add_f32_e32 v86, v78, v72
	v_cndmask_b32_e64 v72, 0, v83, s[18:19]
	v_add_f32_e32 v78, v87, v72
	v_mul_f32_e32 v72, 0x3fb8aa3b, v80
	v_mul_f32_e32 v73, 0x3fb8aa3b, v76
	v_exp_f32_e32 v72, v72
	v_exp_f32_e32 v73, v73
	v_cndmask_b32_e64 v74, 0, v75, s[18:19]
	v_add_f32_e32 v87, v79, v74
	v_rcp_f32_e32 v74, v72
	v_rcp_f32_e32 v75, v73
	v_mul_f32_e32 v76, 0x3fb8aa3b, v77
	v_mul_f32_e32 v77, 0x3fb8aa3b, v78
	v_exp_f32_e32 v76, v76
	v_exp_f32_e32 v77, v77
	s_waitcnt vmcnt(2)
	v_lshlrev_b32_e32 v208, 16, v100
	v_and_b32_e32 v209, 0xffff0000, v100
	v_pk_mul_f32 v[74:75], v[74:75], v[208:209]
	v_lshlrev_b32_e32 v210, 16, v101
	v_pk_mul_f32 v[78:79], v[68:69], v[74:75]
	v_rcp_f32_e32 v68, v76
	v_rcp_f32_e32 v69, v77
	v_and_b32_e32 v211, 0xffff0000, v101
	v_mul_f32_e32 v80, 0x3fb8aa3b, v84
	v_exp_f32_e32 v80, v80
	v_pk_mul_f32 v[82:83], v[68:69], v[210:211]
	v_mul_f32_e32 v69, 0x3fb8aa3b, v81
	v_exp_f32_e32 v81, v69
	v_mul_f32_e32 v69, 0x3fb8aa3b, v86
	v_pk_mul_f32 v[84:85], v[70:71], v[82:83]
	v_exp_f32_e32 v70, v69
	v_mul_f32_e32 v69, 0x3fb8aa3b, v87
	v_exp_f32_e32 v71, v69
	v_rcp_f32_e32 v68, v80
	v_rcp_f32_e32 v69, v81
	v_rcp_f32_e32 v86, v70
	v_rcp_f32_e32 v87, v71
	v_lshlrev_b32_e32 v88, 16, v96
	v_and_b32_e32 v89, 0xffff0000, v96
	v_lshlrev_b32_e32 v90, 16, v97
	v_and_b32_e32 v91, 0xffff0000, v97
	v_lshlrev_b32_e32 v92, 16, v98
	v_and_b32_e32 v93, 0xffff0000, v98
	v_lshlrev_b32_e32 v94, 16, v99
	v_and_b32_e32 v95, 0xffff0000, v99
	v_lshlrev_b32_e32 v212, 16, v102
	v_and_b32_e32 v213, 0xffff0000, v102
	v_lshlrev_b32_e32 v214, 16, v103
	v_and_b32_e32 v215, 0xffff0000, v103
	v_pk_mul_f32 v[72:73], v[72:73], v[88:89]
	v_pk_mul_f32 v[76:77], v[76:77], v[90:91]
	v_pk_mul_f32 v[80:81], v[80:81], v[92:93]
	v_pk_mul_f32 v[88:89], v[68:69], v[212:213]
	v_pk_mul_f32 v[68:69], v[70:71], v[94:95]
	v_pk_mul_f32 v[86:87], v[86:87], v[214:215]
	v_pk_mul_f32 v[90:91], v[64:65], v[88:89]
	v_pk_mul_f32 v[92:93], v[66:67], v[86:87]
	v_cvt_pk_bf16_f32 v64, v72, v73
	v_cvt_pk_bf16_f32 v65, v76, v77
	v_cvt_pk_bf16_f32 v66, v80, v81
	v_cvt_pk_bf16_f32 v67, v68, v69
	v_cvt_pk_bf16_f32 v68, v74, v75
	v_cvt_pk_bf16_f32 v69, v82, v83
	v_cvt_pk_bf16_f32 v70, v88, v89
	v_cvt_pk_bf16_f32 v71, v86, v87
	ds_write_b128 v175, v[64:67]
	ds_write_b128 v175, v[68:71] offset:17408
	v_cvt_pk_bf16_f32 v64, v78, v79
	ds_write_b16 v176, v64 offset:34816
	ds_write_b16_d16_hi v176, v64 offset:34960
	v_cvt_pk_bf16_f32 v64, v84, v85
	ds_write_b16 v176, v64 offset:35104
	ds_write_b16_d16_hi v176, v64 offset:35248
	v_cvt_pk_bf16_f32 v64, v90, v91
	ds_write_b16 v176, v64 offset:35392
	ds_write_b16_d16_hi v176, v64 offset:35536
	v_cvt_pk_bf16_f32 v64, v92, v93
	ds_write_b16 v176, v64 offset:35680
	ds_write_b16_d16_hi v176, v64 offset:35824
	s_waitcnt vmcnt(2)
	ds_write_b16 v176, v104 offset:53248
	ds_write_b16_d16_hi v176, v104 offset:53392
	ds_write_b16 v176, v105 offset:53536
	ds_write_b16_d16_hi v176, v105 offset:53680
	ds_write_b16 v176, v106 offset:53824
	ds_write_b16_d16_hi v176, v106 offset:53968
	ds_write_b16 v176, v107 offset:54112
	ds_write_b16_d16_hi v176, v107 offset:54256
	ds_read_b128 v[64:67], v160
	ds_read_b128 v[80:83], v159
	ds_read_b128 v[72:75], v159 offset:16
	ds_read_b128 v[88:91], v160 offset:16
	ds_read_b128 v[84:87], v177
	ds_read_b128 v[76:79], v177 offset:16
	s_waitcnt lgkmcnt(4)
	v_add_f32_e32 v64, v80, v64
	v_add_f32_e32 v65, v81, v65
	v_add_f32_e32 v66, v82, v66
	v_add_f32_e32 v67, v83, v67
	v_mul_f32_e32 v64, 0x3fb8aa3b, v64
	v_mul_f32_e32 v65, 0x3fb8aa3b, v65
	v_mul_f32_e32 v66, 0x3fb8aa3b, v66
	v_mul_f32_e32 v67, 0x3fb8aa3b, v67
	v_exp_f32_e32 v68, v64
	s_waitcnt lgkmcnt(2)
	v_add_f32_e32 v64, v72, v88
	v_exp_f32_e32 v69, v65
	v_add_f32_e32 v65, v73, v89
	v_exp_f32_e32 v70, v66
	v_add_f32_e32 v66, v74, v90
	v_exp_f32_e32 v71, v67
	v_add_f32_e32 v67, v75, v91
	v_mul_f32_e32 v64, 0x3fb8aa3b, v64
	v_mul_f32_e32 v65, 0x3fb8aa3b, v65
	v_mul_f32_e32 v66, 0x3fb8aa3b, v66
	v_mul_f32_e32 v67, 0x3fb8aa3b, v67
	v_exp_f32_e32 v64, v64
	v_exp_f32_e32 v65, v65
	v_exp_f32_e32 v66, v66
	v_exp_f32_e32 v67, v67
	s_and_saveexec_b64 s[10:11], s[24:25]
	s_cbranch_execz .LBB0_1047
	ds_write_b128 v161, v[68:71]
	ds_write_b128 v161, v[64:67] offset:16
; __device__ __forceinline__ void gla_phase(LAS unsigned char* lds, const bf16* Q, const bf16* K, const bf16* V, const bf16* Z, bf16* OF, bf16* OB,
;                                           const float* wgf, const float* bgf, const float* wgb, const float* bgb, const int wave_s) {
;     ...
;             for (int i = 0; i < 2; ++i) { const int idx = tid + 512 * i, p = idx >> 4, c8 = idx & 15; const int pcol = ((((p >> 3) ^ (c8 & 7)) << 4) + ((p & 7) << 1));
;                 const f32x4 b0 = *(const LAS f32x4*)(Bc + p * 132 + 8 * c8), b1 = *(const LAS f32x4*)(Bc + p * 132 + 8 * c8 + 4);
;                 const f32x4 t00 = *(const LAS f32x4*)(Seg + 8 * c8), t01 = *(const LAS f32x4*)(Seg + 8 * c8 + 4), t10 = *(const LAS f32x4*)(Seg + 128 + 8 * c8), t11 = *(const LAS f32x4*)(Seg + 128 + 8 * c8 + 4);
;                 float qf[8], kf[8], bc[8], dc[8];
;                 qf[0] = bflo(rq[i].x); qf[1] = bfhi(rq[i].x); qf[2] = bflo(rq[i].y); qf[3] = bfhi(rq[i].y); qf[4] = bflo(rq[i].z); qf[5] = bfhi(rq[i].z); qf[6] = bflo(rq[i].w); qf[7] = bfhi(rq[i].w);
;                 kf[0] = bflo(rk[i].x); kf[1] = bfhi(rk[i].x); kf[2] = bflo(rk[i].y); kf[3] = bfhi(rk[i].y); kf[4] = bflo(rk[i].z); kf[5] = bfhi(rk[i].z); kf[6] = bflo(rk[i].w); kf[7] = bfhi(rk[i].w);
; #pragma unroll
;                 for (int e = 0; e < 4; ++e) { bc[e] = b0[e] + (p >= 32 ? t00[e] : 0.f); bc[4 + e] = b1[e] + (p >= 32 ? t01[e] : 0.f); dc[e] = __expf(t00[e] + t10[e]); dc[4 + e] = __expf(t01[e] + t11[e]); }
;                 if (p == 0) { *(LAS f32x4*)(Dec + 8 * c8) = (f32x4){dc[0], dc[1], dc[2], dc[3]}; *(LAS f32x4*)(Dec + 8 * c8 + 4) = (f32x4){dc[4], dc[5], dc[6], dc[7]}; }
;                 float qe[8], ke[8], kn[8];
; #pragma unroll
;                 for (int e = 0; e < 8; ++e) { const float ex = __expf(bc[e]); const float inv = __builtin_amdgcn_rcpf(ex); qe[e] = qf[e] * ex; ke[e] = kf[e] * inv; kn[e] = ke[e] * dc[e]; }
;                 v4u wq, wk; wq.x = cvtpk(qe[0], qe[1]); wq.y = cvtpk(qe[2], qe[3]); wq.z = cvtpk(qe[4], qe[5]); wq.w = cvtpk(qe[6], qe[7]);
;                 wk.x = cvtpk(ke[0], ke[1]); wk.y = cvtpk(ke[2], ke[3]); wk.z = cvtpk(ke[4], ke[5]); wk.w = cvtpk(ke[6], ke[7]);
;                 *(LAS v4u*)(Qe + p * 272 + 16 * c8) = wq; *(LAS v4u*)(Ke + p * 272 + 16 * c8) = wk;
; #pragma unroll
;                 for (int e = 0; e < 8; e += 2) { const unsigned pk = cvtpk(kn[e], kn[e + 1]);
.LBB0_1047:
	s_or_b64 exec, exec, s[10:11]
	v_cndmask_b32_e64 v80, 0, v80, s[22:23]
	v_cndmask_b32_e64 v72, 0, v72, s[22:23]
	s_waitcnt lgkmcnt(1)
	v_add_f32_e32 v80, v84, v80
	s_waitcnt lgkmcnt(0)
	v_add_f32_e32 v84, v76, v72
	v_cndmask_b32_e64 v72, 0, v81, s[22:23]
	v_add_f32_e32 v76, v85, v72
	v_cndmask_b32_e64 v72, 0, v73, s[22:23]
	v_add_f32_e32 v81, v77, v72
	v_cndmask_b32_e64 v72, 0, v82, s[22:23]
	v_add_f32_e32 v77, v86, v72
	v_cndmask_b32_e64 v72, 0, v74, s[22:23]
	v_add_f32_e32 v86, v78, v72
	v_cndmask_b32_e64 v72, 0, v83, s[22:23]
	v_add_f32_e32 v78, v87, v72
	v_mul_f32_e32 v72, 0x3fb8aa3b, v80
	v_mul_f32_e32 v73, 0x3fb8aa3b, v76
	v_exp_f32_e32 v72, v72
	v_exp_f32_e32 v73, v73
	v_cndmask_b32_e64 v74, 0, v75, s[22:23]
	v_add_f32_e32 v87, v79, v74
	v_rcp_f32_e32 v74, v72
	v_rcp_f32_e32 v75, v73
	v_mul_f32_e32 v76, 0x3fb8aa3b, v77
	v_mul_f32_e32 v77, 0x3fb8aa3b, v78
	v_exp_f32_e32 v76, v76
	v_exp_f32_e32 v77, v77
	s_waitcnt vmcnt(2)
	v_lshlrev_b32_e32 v208, 16, v112
	v_and_b32_e32 v209, 0xffff0000, v112
	v_pk_mul_f32 v[74:75], v[74:75], v[208:209]
	v_lshlrev_b32_e32 v210, 16, v113
	v_pk_mul_f32 v[78:79], v[68:69], v[74:75]
	v_rcp_f32_e32 v68, v76
	v_rcp_f32_e32 v69, v77
	v_and_b32_e32 v211, 0xffff0000, v113
	v_mul_f32_e32 v80, 0x3fb8aa3b, v84
	v_exp_f32_e32 v80, v80
	v_pk_mul_f32 v[82:83], v[68:69], v[210:211]
	v_mul_f32_e32 v69, 0x3fb8aa3b, v81
	v_exp_f32_e32 v81, v69
	v_mul_f32_e32 v69, 0x3fb8aa3b, v86
	v_pk_mul_f32 v[84:85], v[70:71], v[82:83]
	v_exp_f32_e32 v70, v69
	v_mul_f32_e32 v69, 0x3fb8aa3b, v87
	v_exp_f32_e32 v71, v69
	v_rcp_f32_e32 v68, v80
	v_rcp_f32_e32 v69, v81
	v_rcp_f32_e32 v86, v70
	v_rcp_f32_e32 v87, v71
	v_lshlrev_b32_e32 v88, 16, v108
	v_and_b32_e32 v89, 0xffff0000, v108
	v_lshlrev_b32_e32 v90, 16, v109
	v_and_b32_e32 v91, 0xffff0000, v109
	v_lshlrev_b32_e32 v92, 16, v110
	v_and_b32_e32 v93, 0xffff0000, v110
	v_lshlrev_b32_e32 v94, 16, v111
	v_and_b32_e32 v95, 0xffff0000, v111
	v_lshlrev_b32_e32 v212, 16, v114
	v_and_b32_e32 v213, 0xffff0000, v114
	v_lshlrev_b32_e32 v214, 16, v115
	v_and_b32_e32 v215, 0xffff0000, v115
	v_pk_mul_f32 v[72:73], v[72:73], v[88:89]
	v_pk_mul_f32 v[76:77], v[76:77], v[90:91]
	v_pk_mul_f32 v[80:81], v[80:81], v[92:93]
	v_pk_mul_f32 v[88:89], v[68:69], v[212:213]
	v_pk_mul_f32 v[68:69], v[70:71], v[94:95]
	v_pk_mul_f32 v[86:87], v[86:87], v[214:215]
	v_pk_mul_f32 v[90:91], v[64:65], v[88:89]
	v_pk_mul_f32 v[92:93], v[66:67], v[86:87]
	v_cvt_pk_bf16_f32 v64, v72, v73
	v_cvt_pk_bf16_f32 v65, v76, v77
	v_cvt_pk_bf16_f32 v66, v80, v81
	v_cvt_pk_bf16_f32 v67, v68, v69
	v_cvt_pk_bf16_f32 v68, v74, v75
	v_cvt_pk_bf16_f32 v69, v82, v83
	v_cvt_pk_bf16_f32 v70, v88, v89
	v_cvt_pk_bf16_f32 v71, v86, v87
	ds_write_b128 v178, v[64:67]
	ds_write_b128 v178, v[68:71] offset:17408
	v_cvt_pk_bf16_f32 v64, v78, v79
	ds_write_b16 v179, v64 offset:34816
	ds_write_b16_d16_hi v179, v64 offset:34960
	v_cvt_pk_bf16_f32 v64, v84, v85
	ds_write_b16 v179, v64 offset:35104
	ds_write_b16_d16_hi v179, v64 offset:35248
	v_cvt_pk_bf16_f32 v64, v90, v91
	ds_write_b16 v179, v64 offset:35392
	ds_write_b16_d16_hi v179, v64 offset:35536
	v_cvt_pk_bf16_f32 v64, v92, v93
	ds_write_b16 v179, v64 offset:35680
	ds_write_b16_d16_hi v179, v64 offset:35824
	s_waitcnt vmcnt(2)
	ds_write_b16 v179, v116 offset:53248
	ds_write_b16_d16_hi v179, v116 offset:53392
	ds_write_b16 v179, v117 offset:53536
	ds_write_b16_d16_hi v179, v117 offset:53680
	ds_write_b16 v179, v118 offset:53824
	ds_write_b16_d16_hi v179, v118 offset:53968
	ds_write_b16 v179, v119 offset:54112
	ds_write_b16_d16_hi v179, v119 offset:54256
	s_and_saveexec_b64 s[10:11], s[14:15]
	ds_write_b128 v201, v[120:123]
	s_or_b64 exec, exec, s[10:11]
	s_cmpk_lt_u32 s7, 0x42
	s_cselect_b64 s[10:11], -1, 0
	s_and_b64 s[60:61], s[14:15], s[10:11]
	s_and_saveexec_b64 s[10:11], s[60:61]
	s_cbranch_execz .LBB0_1051
	s_cmp_lt_u32 s7, 2
	s_movk_i32 s60, 0xff80
	s_cselect_b32 s60, 0x80, s60
	s_cselect_b32 s61, 0xff, s6
	s_cselect_b32 s94, s5, s97
	s_add_i32 s95, s96, s60
	s_sub_i32 s60, s61, s60
	v_add_u32_e32 v64, s95, v151
	v_add_u32_e32 v65, s60, v206
	v_cndmask_b32_e64 v64, v65, v64, s[92:93]
	v_add_u32_e32 v64, s94, v64
	v_ashrrev_i32_e32 v65, 31, v64
	v_lshlrev_b64 v[64:65], 6, v[64:65]
	v_lshl_add_u64 v[64:65], v[146:147], 0, v[64:65]
	global_load_dwordx4 v[120:123], v[64:65], off

; __device__ __forceinline__ unsigned cvtpk(float lo, float hi) { f32x2 v = {lo, hi}; bf16x2_t b = __builtin_convertvector(v, bf16x2_t); return __builtin_bit_cast(unsigned, b); }
; __device__ __forceinline__ void gla_phase(LAS unsigned char* lds, const bf16* Q, const bf16* K, const bf16* V, const bf16* Z, bf16* OF, bf16* OB,
;                                           const float* wgf, const float* bgf, const float* wgb, const float* bgb, const int wave_s) {
;     ...
;             { const size_t row = (size_t)gla_row(n, 32 * wi + r, b, dir); bf16* op = O + row * 1024 + hh * 256 + vh * 128 + 32 * wv + 4 * h;
; #pragma unroll
;               for (int g4 = 0; g4 < 4; ++g4) { v2u w2; w2.x = cvtpk(oT[4 * g4], oT[4 * g4 + 1]); w2.y = cvtpk(oT[4 * g4 + 2], oT[4 * g4 + 3]); *(v2u*)(op + 8 * g4) = w2; } }
.LBB0_1802:
	s_add_i32 s10, s16, 0xffffff00
	s_cmp_lt_u32 s7, 4
	s_cselect_b32 s10, s16, s10
	v_add_u32_e32 v80, s10, v157
	s_cselect_b32 s10, 0xff, s6
	v_sub_u32_e32 v81, s10, v80
	v_cndmask_b32_e64 v80, v81, v80, s[96:97]
	s_cselect_b32 s10, s5, s17
	v_add_u32_e32 v80, s10, v80
	v_ashrrev_i32_e32 v81, 31, v80
	v_lshlrev_b64 v[80:81], 11, v[80:81]
	v_lshl_add_u64 v[80:81], v[150:151], 0, v[80:81]
	v_cvt_pk_bf16_f32 v64, v64, v65
	v_cvt_pk_bf16_f32 v65, v66, v67
	v_cvt_pk_bf16_f32 v66, v68, v69
	v_cvt_pk_bf16_f32 v67, v70, v71
	v_cvt_pk_bf16_f32 v68, v72, v73
	v_cvt_pk_bf16_f32 v69, v74, v75
	v_cvt_pk_bf16_f32 v70, v76, v77
	v_cvt_pk_bf16_f32 v71, v78, v79
	v_mbcnt_lo_u32_b32 v82, -1, 0
	v_mbcnt_hi_u32_b32 v82, -1, v82
	v_and_b32_e32 v82, 32, v82
	v_lshrrev_b32_e32 v82, 2, v82
	v_add_co_u32_e32 v80, vcc, v80, v82
	s_nop 1
	v_addc_co_u32_e32 v81, vcc, 0, v81, vcc
	v_permlane32_swap_b32_e32 v64, v66
	v_permlane32_swap_b32_e32 v65, v67
	v_permlane32_swap_b32_e32 v68, v70
	v_permlane32_swap_b32_e32 v69, v71
	global_store_dwordx4 v[80:81], v[64:67], off
	global_store_dwordx4 v[80:81], v[68:71], off offset:32
	s_add_i32 s16, s16, 64
	s_add_i32 s7, s7, 1
	s_cmpk_eq_i32 s16, 0x1100
	v_subrev_u32_e32 v96, 64, v96
	s_cbranch_scc1 .LBB0_1793

; __device__ __forceinline__ void gla_phase(LAS unsigned char* lds, const bf16* Q, const bf16* K, const bf16* V, const bf16* Z, bf16* OF, bf16* OB,
;                                           const float* wgf, const float* bgf, const float* wgb, const float* bgb, const int wave_s) {
;     ...
;             for (int i = 0; i < 2; ++i) { const int idx = tid + 512 * i, p = idx >> 4, c8 = idx & 15; const int pcol = ((((p >> 3) ^ (c8 & 7)) << 4) + ((p & 7) << 1));
;                 const f32x4 b0 = *(const LAS f32x4*)(Bc + p * 132 + 8 * c8), b1 = *(const LAS f32x4*)(Bc + p * 132 + 8 * c8 + 4);
;                 const f32x4 t00 = *(const LAS f32x4*)(Seg + 8 * c8), t01 = *(const LAS f32x4*)(Seg + 8 * c8 + 4), t10 = *(const LAS f32x4*)(Seg + 128 + 8 * c8), t11 = *(const LAS f32x4*)(Seg + 128 + 8 * c8 + 4);
;                 float qf[8], kf[8], bc[8], dc[8];
;                 qf[0] = bflo(rq[i].x); qf[1] = bfhi(rq[i].x); qf[2] = bflo(rq[i].y); qf[3] = bfhi(rq[i].y); qf[4] = bflo(rq[i].z); qf[5] = bfhi(rq[i].z); qf[6] = bflo(rq[i].w); qf[7] = bfhi(rq[i].w);
;                 kf[0] = bflo(rk[i].x); kf[1] = bfhi(rk[i].x); kf[2] = bflo(rk[i].y); kf[3] = bfhi(rk[i].y); kf[4] = bflo(rk[i].z); kf[5] = bfhi(rk[i].z); kf[6] = bflo(rk[i].w); kf[7] = bfhi(rk[i].w);
; #pragma unroll
;                 for (int e = 0; e < 4; ++e) { bc[e] = b0[e] + (p >= 32 ? t00[e] : 0.f); bc[4 + e] = b1[e] + (p >= 32 ? t01[e] : 0.f); dc[e] = __expf(t00[e] + t10[e]); dc[4 + e] = __expf(t01[e] + t11[e]); }
;                 if (p == 0) { *(LAS f32x4*)(Dec + 8 * c8) = (f32x4){dc[0], dc[1], dc[2], dc[3]}; *(LAS f32x4*)(Dec + 8 * c8 + 4) = (f32x4){dc[4], dc[5], dc[6], dc[7]}; }
;                 float qe[8], ke[8], kn[8];
; #pragma unroll
;                 for (int e = 0; e < 8; ++e) { const float ex = __expf(bc[e]); const float inv = __builtin_amdgcn_rcpf(ex); qe[e] = qf[e] * ex; ke[e] = kf[e] * inv; kn[e] = ke[e] * dc[e]; }
;                 v4u wq, wk; wq.x = cvtpk(qe[0], qe[1]); wq.y = cvtpk(qe[2], qe[3]); wq.z = cvtpk(qe[4], qe[5]); wq.w = cvtpk(qe[6], qe[7]);
;                 wk.x = cvtpk(ke[0], ke[1]); wk.y = cvtpk(ke[2], ke[3]); wk.z = cvtpk(ke[4], ke[5]); wk.w = cvtpk(ke[6], ke[7]);
;                 *(LAS v4u*)(Qe + p * 272 + 16 * c8) = wq; *(LAS v4u*)(Ke + p * 272 + 16 * c8) = wk;
; #pragma unroll
;                 for (int e = 0; e < 8; e += 2) { const unsigned pk = cvtpk(kn[e], kn[e + 1]);
.LBB0_1805:
	s_or_b64 exec, exec, s[10:11]
	v_cndmask_b32_e64 v80, 0, v80, s[22:23]
	v_cndmask_b32_e64 v72, 0, v72, s[22:23]
	s_waitcnt lgkmcnt(1)
	v_add_f32_e32 v80, v84, v80
	s_waitcnt lgkmcnt(0)
	v_add_f32_e32 v84, v76, v72
	v_cndmask_b32_e64 v72, 0, v81, s[22:23]
	v_add_f32_e32 v76, v85, v72
	v_cndmask_b32_e64 v72, 0, v73, s[22:23]
	v_add_f32_e32 v81, v77, v72
	v_cndmask_b32_e64 v72, 0, v82, s[22:23]
	v_add_f32_e32 v77, v86, v72
	v_cndmask_b32_e64 v72, 0, v74, s[22:23]
	v_add_f32_e32 v86, v78, v72
	v_cndmask_b32_e64 v72, 0, v83, s[22:23]
	v_add_f32_e32 v78, v87, v72
	v_mul_f32_e32 v72, 0x3fb8aa3b, v80
	v_mul_f32_e32 v73, 0x3fb8aa3b, v76
	v_exp_f32_e32 v72, v72
	v_exp_f32_e32 v73, v73
	v_cndmask_b32_e64 v74, 0, v75, s[22:23]
	v_add_f32_e32 v87, v79, v74
	v_rcp_f32_e32 v74, v72
	v_rcp_f32_e32 v75, v73
	v_mul_f32_e32 v76, 0x3fb8aa3b, v77
	v_mul_f32_e32 v77, 0x3fb8aa3b, v78
	v_exp_f32_e32 v76, v76
	v_exp_f32_e32 v77, v77
	s_waitcnt vmcnt(2)
	v_lshlrev_b32_e32 v208, 16, v104
	v_and_b32_e32 v209, 0xffff0000, v104
	v_pk_mul_f32 v[74:75], v[74:75], v[208:209]
	v_lshlrev_b32_e32 v210, 16, v105
	v_pk_mul_f32 v[78:79], v[68:69], v[74:75]
	v_rcp_f32_e32 v68, v76
	v_rcp_f32_e32 v69, v77
	v_and_b32_e32 v211, 0xffff0000, v105
	v_mul_f32_e32 v80, 0x3fb8aa3b, v84
	v_exp_f32_e32 v80, v80
	v_pk_mul_f32 v[82:83], v[68:69], v[210:211]
	v_mul_f32_e32 v69, 0x3fb8aa3b, v81
	v_exp_f32_e32 v81, v69
	v_mul_f32_e32 v69, 0x3fb8aa3b, v86
	v_pk_mul_f32 v[84:85], v[70:71], v[82:83]
	v_exp_f32_e32 v70, v69
	v_mul_f32_e32 v69, 0x3fb8aa3b, v87
	v_exp_f32_e32 v71, v69
	v_rcp_f32_e32 v68, v80
	v_rcp_f32_e32 v69, v81
	v_rcp_f32_e32 v86, v70
	v_rcp_f32_e32 v87, v71
	v_lshlrev_b32_e32 v88, 16, v100
	v_and_b32_e32 v89, 0xffff0000, v100
	v_lshlrev_b32_e32 v90, 16, v101
	v_and_b32_e32 v91, 0xffff0000, v101
	v_lshlrev_b32_e32 v92, 16, v102
	v_and_b32_e32 v93, 0xffff0000, v102
	v_lshlrev_b32_e32 v94, 16, v103
	v_and_b32_e32 v95, 0xffff0000, v103
	v_lshlrev_b32_e32 v212, 16, v106
	v_and_b32_e32 v213, 0xffff0000, v106
	v_lshlrev_b32_e32 v214, 16, v107
	v_and_b32_e32 v215, 0xffff0000, v107
	v_pk_mul_f32 v[72:73], v[72:73], v[88:89]
	v_pk_mul_f32 v[76:77], v[76:77], v[90:91]
	v_pk_mul_f32 v[80:81], v[80:81], v[92:93]
	v_pk_mul_f32 v[88:89], v[68:69], v[212:213]
	v_pk_mul_f32 v[68:69], v[70:71], v[94:95]
	v_pk_mul_f32 v[86:87], v[86:87], v[214:215]
	v_pk_mul_f32 v[90:91], v[64:65], v[88:89]
	v_pk_mul_f32 v[92:93], v[66:67], v[86:87]
	v_cvt_pk_bf16_f32 v64, v72, v73
	v_cvt_pk_bf16_f32 v65, v76, v77
	v_cvt_pk_bf16_f32 v66, v80, v81
	v_cvt_pk_bf16_f32 v67, v68, v69
	v_cvt_pk_bf16_f32 v68, v74, v75
	v_cvt_pk_bf16_f32 v69, v82, v83
	v_cvt_pk_bf16_f32 v70, v88, v89
	v_cvt_pk_bf16_f32 v71, v86, v87
	ds_write_b128 v177, v[64:67]
	ds_write_b128 v177, v[68:71] offset:17408
	v_cvt_pk_bf16_f32 v64, v78, v79
	ds_write_b16 v178, v64 offset:34816
	ds_write_b16_d16_hi v178, v64 offset:34960
	v_cvt_pk_bf16_f32 v64, v84, v85
	ds_write_b16 v178, v64 offset:35104
	ds_write_b16_d16_hi v178, v64 offset:35248
	v_cvt_pk_bf16_f32 v64, v90, v91
	ds_write_b16 v178, v64 offset:35392
	ds_write_b16_d16_hi v178, v64 offset:35536
	v_cvt_pk_bf16_f32 v64, v92, v93
	ds_write_b16 v178, v64 offset:35680
	ds_write_b16_d16_hi v178, v64 offset:35824
	s_waitcnt vmcnt(2)
	ds_write_b16 v178, v108 offset:53248
	ds_write_b16_d16_hi v178, v108 offset:53392
	ds_write_b16 v178, v109 offset:53536
	ds_write_b16_d16_hi v178, v109 offset:53680
	ds_write_b16 v178, v110 offset:53824
	ds_write_b16_d16_hi v178, v110 offset:53968
	ds_write_b16 v178, v111 offset:54112
	ds_write_b16_d16_hi v178, v111 offset:54256
	ds_read_b128 v[64:67], v162
	ds_read_b128 v[80:83], v161
	ds_read_b128 v[72:75], v161 offset:16
	ds_read_b128 v[88:91], v162 offset:16
	ds_read_b128 v[84:87], v179
	ds_read_b128 v[76:79], v179 offset:16
	s_waitcnt lgkmcnt(4)
	v_add_f32_e32 v64, v80, v64
	v_add_f32_e32 v65, v81, v65
	v_add_f32_e32 v66, v82, v66
	v_add_f32_e32 v67, v83, v67
	v_mul_f32_e32 v64, 0x3fb8aa3b, v64
	v_mul_f32_e32 v65, 0x3fb8aa3b, v65
	v_mul_f32_e32 v66, 0x3fb8aa3b, v66
	v_mul_f32_e32 v67, 0x3fb8aa3b, v67
	v_exp_f32_e32 v68, v64
	s_waitcnt lgkmcnt(2)
	v_add_f32_e32 v64, v72, v88
	v_exp_f32_e32 v69, v65
	v_add_f32_e32 v65, v73, v89
	v_exp_f32_e32 v70, v66
	v_add_f32_e32 v66, v74, v90
	v_exp_f32_e32 v71, v67
	v_add_f32_e32 v67, v75, v91
	v_mul_f32_e32 v64, 0x3fb8aa3b, v64
	v_mul_f32_e32 v65, 0x3fb8aa3b, v65
	v_mul_f32_e32 v66, 0x3fb8aa3b, v66
	v_mul_f32_e32 v67, 0x3fb8aa3b, v67
	v_exp_f32_e32 v64, v64
	v_exp_f32_e32 v65, v65
	v_exp_f32_e32 v66, v66
	v_exp_f32_e32 v67, v67
	s_and_saveexec_b64 s[10:11], s[28:29]
	s_cbranch_execz .LBB0_1807
	ds_write_b128 v163, v[68:71]
	ds_write_b128 v163, v[64:67] offset:16
; #define LAS __attribute__((address_space(3)))
; __device__ __forceinline__ unsigned cvtpk(float lo, float hi) { f32x2 v = {lo, hi}; bf16x2_t b = __builtin_convertvector(v, bf16x2_t); return __builtin_bit_cast(unsigned, b); }
; #define GLA_LOADZ(n) do { if (tid < 128) { const size_t row = (size_t)gla_row((n), tid >> 1, b, dir); rz = *(const v4u*)(Z + row * 32 + dir * 16 + 8 * (tid & 1)); } } while (0)
; #define GLA_ZSTORE() do { if (tid < 128) *(LAS v4u*)(Zs + (tid >> 1) * 32 + 16 * (tid & 1)) = rz; } while (0)
; __device__ __forceinline__ void gla_phase(LAS unsigned char* lds, const bf16* Q, const bf16* K, const bf16* V, const bf16* Z, bf16* OF, bf16* OB,
;                                           const float* wgf, const float* bgf, const float* wgb, const float* bgb, const int wave_s) {
;     ...
;                 for (int e = 0; e < 8; ++e) { const float ex = __expf(bc[e]); const float inv = __builtin_amdgcn_rcpf(ex); qe[e] = qf[e] * ex; ke[e] = kf[e] * inv; kn[e] = ke[e] * dc[e]; }
;                 v4u wq, wk; wq.x = cvtpk(qe[0], qe[1]); wq.y = cvtpk(qe[2], qe[3]); wq.z = cvtpk(qe[4], qe[5]); wq.w = cvtpk(qe[6], qe[7]);
;                 wk.x = cvtpk(ke[0], ke[1]); wk.y = cvtpk(ke[2], ke[3]); wk.z = cvtpk(ke[4], ke[5]); wk.w = cvtpk(ke[6], ke[7]);
;                 *(LAS v4u*)(Qe + p * 272 + 16 * c8) = wq; *(LAS v4u*)(Ke + p * 272 + 16 * c8) = wk;
; #pragma unroll
;                 for (int e = 0; e < 8; e += 2) { const unsigned pk = cvtpk(kn[e], kn[e + 1]);
;                     *(LAS unsigned short*)(KT + (8 * c8 + e) * 144 + pcol) = (unsigned short)(pk & 0xffffu); *(LAS unsigned short*)(KT + (8 * c8 + e + 1) * 144 + pcol) = (unsigned short)(pk >> 16); }
;                 const unsigned vv[4] = {rv[i].x, rv[i].y, rv[i].z, rv[i].w};
; #pragma unroll
;                 for (int e = 0; e < 4; ++e) { *(LAS unsigned short*)(VT + (8 * c8 + 2 * e) * 144 + pcol) = (unsigned short)(vv[e] & 0xffffu); *(LAS unsigned short*)(VT + (8 * c8 + 2 * e + 1) * 144 + pcol) = (unsigned short)(vv[e] >> 16); }
;                 asm volatile("" ::: "memory");
;             }
;             GLA_ZSTORE();
;             if (n + 2 < NCHUNK) GLA_LOADZ(n + 2);
.LBB0_1807:
	s_or_b64 exec, exec, s[10:11]
	v_cndmask_b32_e64 v80, 0, v80, s[26:27]
	v_cndmask_b32_e64 v72, 0, v72, s[26:27]
	s_waitcnt lgkmcnt(1)
	v_add_f32_e32 v80, v84, v80
	s_waitcnt lgkmcnt(0)
	v_add_f32_e32 v84, v76, v72
	v_cndmask_b32_e64 v72, 0, v81, s[26:27]
	v_add_f32_e32 v76, v85, v72
	v_cndmask_b32_e64 v72, 0, v73, s[26:27]
	v_add_f32_e32 v81, v77, v72
	v_cndmask_b32_e64 v72, 0, v82, s[26:27]
	v_add_f32_e32 v77, v86, v72
	v_cndmask_b32_e64 v72, 0, v74, s[26:27]
	v_add_f32_e32 v86, v78, v72
	v_cndmask_b32_e64 v72, 0, v83, s[26:27]
	v_add_f32_e32 v78, v87, v72
	v_mul_f32_e32 v72, 0x3fb8aa3b, v80
	v_mul_f32_e32 v73, 0x3fb8aa3b, v76
	v_exp_f32_e32 v72, v72
	v_exp_f32_e32 v73, v73
	v_cndmask_b32_e64 v74, 0, v75, s[26:27]
	v_add_f32_e32 v87, v79, v74
	v_rcp_f32_e32 v74, v72
	v_rcp_f32_e32 v75, v73
	v_mul_f32_e32 v76, 0x3fb8aa3b, v77
	v_mul_f32_e32 v77, 0x3fb8aa3b, v78
	v_exp_f32_e32 v76, v76
	v_exp_f32_e32 v77, v77
	s_waitcnt vmcnt(2)
	v_lshlrev_b32_e32 v208, 16, v116
	v_and_b32_e32 v209, 0xffff0000, v116
	v_pk_mul_f32 v[74:75], v[74:75], v[208:209]
	v_lshlrev_b32_e32 v210, 16, v117
	v_pk_mul_f32 v[78:79], v[68:69], v[74:75]
	v_rcp_f32_e32 v68, v76
	v_rcp_f32_e32 v69, v77
	v_and_b32_e32 v211, 0xffff0000, v117
	v_mul_f32_e32 v80, 0x3fb8aa3b, v84
	v_exp_f32_e32 v80, v80
	v_pk_mul_f32 v[82:83], v[68:69], v[210:211]
	v_mul_f32_e32 v69, 0x3fb8aa3b, v81
	v_exp_f32_e32 v81, v69
	v_mul_f32_e32 v69, 0x3fb8aa3b, v86
	v_pk_mul_f32 v[84:85], v[70:71], v[82:83]
	v_exp_f32_e32 v70, v69
	v_mul_f32_e32 v69, 0x3fb8aa3b, v87
	v_exp_f32_e32 v71, v69
	v_rcp_f32_e32 v68, v80
	v_rcp_f32_e32 v69, v81
	v_rcp_f32_e32 v86, v70
	v_rcp_f32_e32 v87, v71
	v_lshlrev_b32_e32 v88, 16, v112
	v_and_b32_e32 v89, 0xffff0000, v112
	v_lshlrev_b32_e32 v90, 16, v113
	v_and_b32_e32 v91, 0xffff0000, v113
	v_lshlrev_b32_e32 v92, 16, v114
	v_and_b32_e32 v93, 0xffff0000, v114
	v_lshlrev_b32_e32 v94, 16, v115
	v_and_b32_e32 v95, 0xffff0000, v115
	v_lshlrev_b32_e32 v212, 16, v118
	v_and_b32_e32 v213, 0xffff0000, v118
	v_lshlrev_b32_e32 v214, 16, v119
	v_and_b32_e32 v215, 0xffff0000, v119
	v_pk_mul_f32 v[72:73], v[72:73], v[88:89]
	v_pk_mul_f32 v[76:77], v[76:77], v[90:91]
	v_pk_mul_f32 v[80:81], v[80:81], v[92:93]
	v_pk_mul_f32 v[88:89], v[68:69], v[212:213]
	v_pk_mul_f32 v[68:69], v[70:71], v[94:95]
	v_pk_mul_f32 v[86:87], v[86:87], v[214:215]
	v_pk_mul_f32 v[90:91], v[64:65], v[88:89]
	v_pk_mul_f32 v[92:93], v[66:67], v[86:87]
	v_cvt_pk_bf16_f32 v64, v72, v73
	v_cvt_pk_bf16_f32 v65, v76, v77
	v_cvt_pk_bf16_f32 v66, v80, v81
	v_cvt_pk_bf16_f32 v67, v68, v69
	v_cvt_pk_bf16_f32 v68, v74, v75
	v_cvt_pk_bf16_f32 v69, v82, v83
	v_cvt_pk_bf16_f32 v70, v88, v89
	v_cvt_pk_bf16_f32 v71, v86, v87
	ds_write_b128 v180, v[64:67]
	ds_write_b128 v180, v[68:71] offset:17408
	v_cvt_pk_bf16_f32 v64, v78, v79
	ds_write_b16 v181, v64 offset:34816
	ds_write_b16_d16_hi v181, v64 offset:34960
	v_cvt_pk_bf16_f32 v64, v84, v85
	ds_write_b16 v181, v64 offset:35104
	ds_write_b16_d16_hi v181, v64 offset:35248
	v_cvt_pk_bf16_f32 v64, v90, v91
	ds_write_b16 v181, v64 offset:35392
	ds_write_b16_d16_hi v181, v64 offset:35536
	v_cvt_pk_bf16_f32 v64, v92, v93
	ds_write_b16 v181, v64 offset:35680
	ds_write_b16_d16_hi v181, v64 offset:35824
	s_waitcnt vmcnt(2)
	ds_write_b16 v181, v120 offset:53248
	ds_write_b16_d16_hi v181, v120 offset:53392
	ds_write_b16 v181, v121 offset:53536
	ds_write_b16_d16_hi v181, v121 offset:53680
	ds_write_b16 v181, v122 offset:53824
	ds_write_b16_d16_hi v181, v122 offset:53968
	ds_write_b16 v181, v123 offset:54112
	ds_write_b16_d16_hi v181, v123 offset:54256
	s_and_saveexec_b64 s[10:11], s[18:19]
	ds_write_b128 v203, v[124:127]
	s_or_b64 exec, exec, s[10:11]
	s_cmpk_lt_u32 s7, 0x42
	s_cselect_b64 s[10:11], -1, 0
	s_and_b64 s[12:13], s[18:19], s[10:11]
	s_and_saveexec_b64 s[10:11], s[12:13]
	s_cbranch_execz .LBB0_1811
	s_cmp_lt_u32 s7, 2
	s_movk_i32 s12, 0xff80
	s_cselect_b32 s12, 0x80, s12
	s_cselect_b32 s13, 0xff, s6
	s_cselect_b32 vcc_lo, s5, s17
	s_add_i32 vcc_hi, s16, s12
	s_sub_i32 s12, s13, s12
	v_add_u32_e32 v64, vcc_hi, v153
	v_add_u32_e32 v65, s12, v96
	v_cndmask_b32_e64 v64, v65, v64, s[96:97]
	v_add_u32_e32 v64, vcc_lo, v64
	v_ashrrev_i32_e32 v65, 31, v64
	v_lshlrev_b64 v[64:65], 6, v[64:65]
	v_lshl_add_u64 v[64:65], v[98:99], 0, v[64:65]
	global_load_dwordx4 v[124:127], v[64:65], off

; __device__ __forceinline__ unsigned cvtpk(float lo, float hi) { f32x2 v = {lo, hi}; bf16x2_t b = __builtin_convertvector(v, bf16x2_t); return __builtin_bit_cast(unsigned, b); }
; __device__ __forceinline__ void gla_phase(LAS unsigned char* lds, const bf16* Q, const bf16* K, const bf16* V, const bf16* Z, bf16* OF, bf16* OB,
;                                           const float* wgf, const float* bgf, const float* wgb, const float* bgb, const int wave_s) {
;     ...
;             { const size_t row = (size_t)gla_row(n, 32 * wi + r, b, dir); bf16* op = O + row * 1024 + hh * 256 + vh * 128 + 32 * wv + 4 * h;
; #pragma unroll
;               for (int g4 = 0; g4 < 4; ++g4) { v2u w2; w2.x = cvtpk(oT[4 * g4], oT[4 * g4 + 1]); w2.y = cvtpk(oT[4 * g4 + 2], oT[4 * g4 + 3]); *(v2u*)(op + 8 * g4) = w2; } }
.LBB0_2554:
	s_add_i32 s0, s86, 0xffffff00
	s_cmp_lt_u32 s95, 4
	s_cselect_b32 s0, s86, s0
	v_add_u32_e32 v80, s0, v157
	s_cselect_b32 s0, 0xff, s94
	v_sub_u32_e32 v81, s0, v80
	v_cndmask_b32_e64 v80, v81, v80, s[82:83]
	s_cselect_b32 s0, s93, s87
	v_add_u32_e32 v80, s0, v80
	v_ashrrev_i32_e32 v81, 31, v80
	v_lshlrev_b64 v[80:81], 11, v[80:81]
	v_lshl_add_u64 v[80:81], v[150:151], 0, v[80:81]
	v_cvt_pk_bf16_f32 v64, v64, v65
	v_cvt_pk_bf16_f32 v65, v66, v67
	v_cvt_pk_bf16_f32 v66, v68, v69
	v_cvt_pk_bf16_f32 v67, v70, v71
	v_cvt_pk_bf16_f32 v68, v72, v73
	v_cvt_pk_bf16_f32 v69, v74, v75
	v_cvt_pk_bf16_f32 v70, v76, v77
	v_cvt_pk_bf16_f32 v71, v78, v79
	v_mbcnt_lo_u32_b32 v82, -1, 0
	v_mbcnt_hi_u32_b32 v82, -1, v82
	v_and_b32_e32 v82, 32, v82
	v_lshrrev_b32_e32 v82, 2, v82
	v_add_co_u32_e32 v80, vcc, v80, v82
	s_nop 1
	v_addc_co_u32_e32 v81, vcc, 0, v81, vcc
	v_permlane32_swap_b32_e32 v64, v66
	v_permlane32_swap_b32_e32 v65, v67
	v_permlane32_swap_b32_e32 v68, v70
	v_permlane32_swap_b32_e32 v69, v71
	global_store_dwordx4 v[80:81], v[64:67], off
	global_store_dwordx4 v[80:81], v[68:71], off offset:32
	s_add_i32 s86, s86, 64
	s_add_i32 s95, s95, 1
	s_cmpk_eq_i32 s86, 0x1100
	v_subrev_u32_e32 v96, 64, v96
	s_cbranch_scc1 .LBB0_2545

; __device__ __forceinline__ void gla_phase(LAS unsigned char* lds, const bf16* Q, const bf16* K, const bf16* V, const bf16* Z, bf16* OF, bf16* OB,
;                                           const float* wgf, const float* bgf, const float* wgb, const float* bgb, const int wave_s) {
;     ...
;             for (int i = 0; i < 2; ++i) { const int idx = tid + 512 * i, p = idx >> 4, c8 = idx & 15; const int pcol = ((((p >> 3) ^ (c8 & 7)) << 4) + ((p & 7) << 1));
;                 const f32x4 b0 = *(const LAS f32x4*)(Bc + p * 132 + 8 * c8), b1 = *(const LAS f32x4*)(Bc + p * 132 + 8 * c8 + 4);
;                 const f32x4 t00 = *(const LAS f32x4*)(Seg + 8 * c8), t01 = *(const LAS f32x4*)(Seg + 8 * c8 + 4), t10 = *(const LAS f32x4*)(Seg + 128 + 8 * c8), t11 = *(const LAS f32x4*)(Seg + 128 + 8 * c8 + 4);
;                 float qf[8], kf[8], bc[8], dc[8];
;                 qf[0] = bflo(rq[i].x); qf[1] = bfhi(rq[i].x); qf[2] = bflo(rq[i].y); qf[3] = bfhi(rq[i].y); qf[4] = bflo(rq[i].z); qf[5] = bfhi(rq[i].z); qf[6] = bflo(rq[i].w); qf[7] = bfhi(rq[i].w);
;                 kf[0] = bflo(rk[i].x); kf[1] = bfhi(rk[i].x); kf[2] = bflo(rk[i].y); kf[3] = bfhi(rk[i].y); kf[4] = bflo(rk[i].z); kf[5] = bfhi(rk[i].z); kf[6] = bflo(rk[i].w); kf[7] = bfhi(rk[i].w);
; #pragma unroll
;                 for (int e = 0; e < 4; ++e) { bc[e] = b0[e] + (p >= 32 ? t00[e] : 0.f); bc[4 + e] = b1[e] + (p >= 32 ? t01[e] : 0.f); dc[e] = __expf(t00[e] + t10[e]); dc[4 + e] = __expf(t01[e] + t11[e]); }
;                 if (p == 0) { *(LAS f32x4*)(Dec + 8 * c8) = (f32x4){dc[0], dc[1], dc[2], dc[3]}; *(LAS f32x4*)(Dec + 8 * c8 + 4) = (f32x4){dc[4], dc[5], dc[6], dc[7]}; }
;                 float qe[8], ke[8], kn[8];
; #pragma unroll
;                 for (int e = 0; e < 8; ++e) { const float ex = __expf(bc[e]); const float inv = __builtin_amdgcn_rcpf(ex); qe[e] = qf[e] * ex; ke[e] = kf[e] * inv; kn[e] = ke[e] * dc[e]; }
;                 v4u wq, wk; wq.x = cvtpk(qe[0], qe[1]); wq.y = cvtpk(qe[2], qe[3]); wq.z = cvtpk(qe[4], qe[5]); wq.w = cvtpk(qe[6], qe[7]);
;                 wk.x = cvtpk(ke[0], ke[1]); wk.y = cvtpk(ke[2], ke[3]); wk.z = cvtpk(ke[4], ke[5]); wk.w = cvtpk(ke[6], ke[7]);
;                 *(LAS v4u*)(Qe + p * 272 + 16 * c8) = wq; *(LAS v4u*)(Ke + p * 272 + 16 * c8) = wk;
; #pragma unroll
;                 for (int e = 0; e < 8; e += 2) { const unsigned pk = cvtpk(kn[e], kn[e + 1]);
.LBB0_2557:
	s_or_b64 exec, exec, s[0:1]
	v_cndmask_b32_e64 v80, 0, v80, s[8:9]
	v_cndmask_b32_e64 v72, 0, v72, s[8:9]
	s_waitcnt lgkmcnt(1)
	v_add_f32_e32 v80, v84, v80
	s_waitcnt lgkmcnt(0)
	v_add_f32_e32 v84, v76, v72
	v_cndmask_b32_e64 v72, 0, v81, s[8:9]
	v_add_f32_e32 v76, v85, v72
	v_cndmask_b32_e64 v72, 0, v73, s[8:9]
	v_add_f32_e32 v81, v77, v72
	v_cndmask_b32_e64 v72, 0, v82, s[8:9]
	v_add_f32_e32 v77, v86, v72
	v_cndmask_b32_e64 v72, 0, v74, s[8:9]
	v_add_f32_e32 v86, v78, v72
	v_cndmask_b32_e64 v72, 0, v83, s[8:9]
	v_add_f32_e32 v78, v87, v72
	v_mul_f32_e32 v72, 0x3fb8aa3b, v80
	v_mul_f32_e32 v73, 0x3fb8aa3b, v76
	v_exp_f32_e32 v72, v72
	v_exp_f32_e32 v73, v73
	v_cndmask_b32_e64 v74, 0, v75, s[8:9]
	v_add_f32_e32 v87, v79, v74
	v_rcp_f32_e32 v74, v72
	v_rcp_f32_e32 v75, v73
	v_mul_f32_e32 v76, 0x3fb8aa3b, v77
	v_mul_f32_e32 v77, 0x3fb8aa3b, v78
	v_exp_f32_e32 v76, v76
	v_exp_f32_e32 v77, v77
	s_waitcnt vmcnt(2)
	v_lshlrev_b32_e32 v208, 16, v104
	v_and_b32_e32 v209, 0xffff0000, v104
	v_pk_mul_f32 v[74:75], v[74:75], v[208:209]
	v_lshlrev_b32_e32 v210, 16, v105
	v_pk_mul_f32 v[78:79], v[68:69], v[74:75]
	v_rcp_f32_e32 v68, v76
	v_rcp_f32_e32 v69, v77
	v_and_b32_e32 v211, 0xffff0000, v105
	v_mul_f32_e32 v80, 0x3fb8aa3b, v84
	v_exp_f32_e32 v80, v80
	v_pk_mul_f32 v[82:83], v[68:69], v[210:211]
	v_mul_f32_e32 v69, 0x3fb8aa3b, v81
	v_exp_f32_e32 v81, v69
	v_mul_f32_e32 v69, 0x3fb8aa3b, v86
	v_pk_mul_f32 v[84:85], v[70:71], v[82:83]
	v_exp_f32_e32 v70, v69
	v_mul_f32_e32 v69, 0x3fb8aa3b, v87
	v_exp_f32_e32 v71, v69
	v_rcp_f32_e32 v68, v80
	v_rcp_f32_e32 v69, v81
	v_rcp_f32_e32 v86, v70
	v_rcp_f32_e32 v87, v71
	v_lshlrev_b32_e32 v88, 16, v100
	v_and_b32_e32 v89, 0xffff0000, v100
	v_lshlrev_b32_e32 v90, 16, v101
	v_and_b32_e32 v91, 0xffff0000, v101
	v_lshlrev_b32_e32 v92, 16, v102
	v_and_b32_e32 v93, 0xffff0000, v102
	v_lshlrev_b32_e32 v94, 16, v103
	v_and_b32_e32 v95, 0xffff0000, v103
	v_lshlrev_b32_e32 v212, 16, v106
	v_and_b32_e32 v213, 0xffff0000, v106
	v_lshlrev_b32_e32 v214, 16, v107
	v_and_b32_e32 v215, 0xffff0000, v107
	v_pk_mul_f32 v[72:73], v[72:73], v[88:89]
	v_pk_mul_f32 v[76:77], v[76:77], v[90:91]
	v_pk_mul_f32 v[80:81], v[80:81], v[92:93]
	v_pk_mul_f32 v[88:89], v[68:69], v[212:213]
	v_pk_mul_f32 v[68:69], v[70:71], v[94:95]
	v_pk_mul_f32 v[86:87], v[86:87], v[214:215]
	v_pk_mul_f32 v[90:91], v[64:65], v[88:89]
	v_pk_mul_f32 v[92:93], v[66:67], v[86:87]
	v_cvt_pk_bf16_f32 v64, v72, v73
	v_cvt_pk_bf16_f32 v65, v76, v77
	v_cvt_pk_bf16_f32 v66, v80, v81
	v_cvt_pk_bf16_f32 v67, v68, v69
	v_cvt_pk_bf16_f32 v68, v74, v75
	v_cvt_pk_bf16_f32 v69, v82, v83
	v_cvt_pk_bf16_f32 v70, v88, v89
	v_cvt_pk_bf16_f32 v71, v86, v87
	ds_write_b128 v177, v[64:67]
	ds_write_b128 v177, v[68:71] offset:17408
	v_cvt_pk_bf16_f32 v64, v78, v79
	ds_write_b16 v178, v64 offset:34816
	ds_write_b16_d16_hi v178, v64 offset:34960
	v_cvt_pk_bf16_f32 v64, v84, v85
	ds_write_b16 v178, v64 offset:35104
	ds_write_b16_d16_hi v178, v64 offset:35248
	v_cvt_pk_bf16_f32 v64, v90, v91
	ds_write_b16 v178, v64 offset:35392
	ds_write_b16_d16_hi v178, v64 offset:35536
	v_cvt_pk_bf16_f32 v64, v92, v93
	ds_write_b16 v178, v64 offset:35680
	ds_write_b16_d16_hi v178, v64 offset:35824
	s_waitcnt vmcnt(2)
	ds_write_b16 v178, v108 offset:53248
	ds_write_b16_d16_hi v178, v108 offset:53392
	ds_write_b16 v178, v109 offset:53536
	ds_write_b16_d16_hi v178, v109 offset:53680
	ds_write_b16 v178, v110 offset:53824
	ds_write_b16_d16_hi v178, v110 offset:53968
	ds_write_b16 v178, v111 offset:54112
	ds_write_b16_d16_hi v178, v111 offset:54256
	ds_read_b128 v[64:67], v162
	ds_read_b128 v[80:83], v161
	ds_read_b128 v[72:75], v161 offset:16
	ds_read_b128 v[88:91], v162 offset:16
	ds_read_b128 v[84:87], v179
	ds_read_b128 v[76:79], v179 offset:16
	s_waitcnt lgkmcnt(4)
	v_add_f32_e32 v64, v80, v64
	v_add_f32_e32 v65, v81, v65
	v_add_f32_e32 v66, v82, v66
	v_add_f32_e32 v67, v83, v67
	v_mul_f32_e32 v64, 0x3fb8aa3b, v64
	v_mul_f32_e32 v65, 0x3fb8aa3b, v65
	v_mul_f32_e32 v66, 0x3fb8aa3b, v66
	v_mul_f32_e32 v67, 0x3fb8aa3b, v67
	v_exp_f32_e32 v68, v64
	s_waitcnt lgkmcnt(2)
	v_add_f32_e32 v64, v72, v88
	v_exp_f32_e32 v69, v65
	v_add_f32_e32 v65, v73, v89
	v_exp_f32_e32 v70, v66
	v_add_f32_e32 v66, v74, v90
	v_exp_f32_e32 v71, v67
	v_add_f32_e32 v67, v75, v91
	v_mul_f32_e32 v64, 0x3fb8aa3b, v64
	v_mul_f32_e32 v65, 0x3fb8aa3b, v65
	v_mul_f32_e32 v66, 0x3fb8aa3b, v66
	v_mul_f32_e32 v67, 0x3fb8aa3b, v67
	v_exp_f32_e32 v64, v64
	v_exp_f32_e32 v65, v65
	v_exp_f32_e32 v66, v66
	v_exp_f32_e32 v67, v67
	s_and_saveexec_b64 s[0:1], s[14:15]
	s_cbranch_execz .LBB0_2559
	ds_write_b128 v163, v[68:71]
	ds_write_b128 v163, v[64:67] offset:16
; #define LAS __attribute__((address_space(3)))
; __device__ __forceinline__ unsigned cvtpk(float lo, float hi) { f32x2 v = {lo, hi}; bf16x2_t b = __builtin_convertvector(v, bf16x2_t); return __builtin_bit_cast(unsigned, b); }
; #define GLA_LOADZ(n) do { if (tid < 128) { const size_t row = (size_t)gla_row((n), tid >> 1, b, dir); rz = *(const v4u*)(Z + row * 32 + dir * 16 + 8 * (tid & 1)); } } while (0)
; #define GLA_ZSTORE() do { if (tid < 128) *(LAS v4u*)(Zs + (tid >> 1) * 32 + 16 * (tid & 1)) = rz; } while (0)
; __device__ __forceinline__ void gla_phase(LAS unsigned char* lds, const bf16* Q, const bf16* K, const bf16* V, const bf16* Z, bf16* OF, bf16* OB,
;                                           const float* wgf, const float* bgf, const float* wgb, const float* bgb, const int wave_s) {
;     ...
;                 for (int e = 0; e < 8; ++e) { const float ex = __expf(bc[e]); const float inv = __builtin_amdgcn_rcpf(ex); qe[e] = qf[e] * ex; ke[e] = kf[e] * inv; kn[e] = ke[e] * dc[e]; }
;                 v4u wq, wk; wq.x = cvtpk(qe[0], qe[1]); wq.y = cvtpk(qe[2], qe[3]); wq.z = cvtpk(qe[4], qe[5]); wq.w = cvtpk(qe[6], qe[7]);
;                 wk.x = cvtpk(ke[0], ke[1]); wk.y = cvtpk(ke[2], ke[3]); wk.z = cvtpk(ke[4], ke[5]); wk.w = cvtpk(ke[6], ke[7]);
;                 *(LAS v4u*)(Qe + p * 272 + 16 * c8) = wq; *(LAS v4u*)(Ke + p * 272 + 16 * c8) = wk;
; #pragma unroll
;                 for (int e = 0; e < 8; e += 2) { const unsigned pk = cvtpk(kn[e], kn[e + 1]);
;                     *(LAS unsigned short*)(KT + (8 * c8 + e) * 144 + pcol) = (unsigned short)(pk & 0xffffu); *(LAS unsigned short*)(KT + (8 * c8 + e + 1) * 144 + pcol) = (unsigned short)(pk >> 16); }
;                 const unsigned vv[4] = {rv[i].x, rv[i].y, rv[i].z, rv[i].w};
; #pragma unroll
;                 for (int e = 0; e < 4; ++e) { *(LAS unsigned short*)(VT + (8 * c8 + 2 * e) * 144 + pcol) = (unsigned short)(vv[e] & 0xffffu); *(LAS unsigned short*)(VT + (8 * c8 + 2 * e + 1) * 144 + pcol) = (unsigned short)(vv[e] >> 16); }
;                 asm volatile("" ::: "memory");
;             }
;             GLA_ZSTORE();
;             if (n + 2 < NCHUNK) GLA_LOADZ(n + 2);
.LBB0_2559:
	s_or_b64 exec, exec, s[0:1]
	v_cndmask_b32_e64 v80, 0, v80, s[12:13]
	v_cndmask_b32_e64 v72, 0, v72, s[12:13]
	s_waitcnt lgkmcnt(1)
	v_add_f32_e32 v80, v84, v80
	s_waitcnt lgkmcnt(0)
	v_add_f32_e32 v84, v76, v72
	v_cndmask_b32_e64 v72, 0, v81, s[12:13]
	v_add_f32_e32 v76, v85, v72
	v_cndmask_b32_e64 v72, 0, v73, s[12:13]
	v_add_f32_e32 v81, v77, v72
	v_cndmask_b32_e64 v72, 0, v82, s[12:13]
	v_add_f32_e32 v77, v86, v72
	v_cndmask_b32_e64 v72, 0, v74, s[12:13]
	v_add_f32_e32 v86, v78, v72
	v_cndmask_b32_e64 v72, 0, v83, s[12:13]
	v_add_f32_e32 v78, v87, v72
	v_mul_f32_e32 v72, 0x3fb8aa3b, v80
	v_mul_f32_e32 v73, 0x3fb8aa3b, v76
	v_exp_f32_e32 v72, v72
	v_exp_f32_e32 v73, v73
	v_cndmask_b32_e64 v74, 0, v75, s[12:13]
	v_add_f32_e32 v87, v79, v74
	v_rcp_f32_e32 v74, v72
	v_rcp_f32_e32 v75, v73
	v_mul_f32_e32 v76, 0x3fb8aa3b, v77
	v_mul_f32_e32 v77, 0x3fb8aa3b, v78
	v_exp_f32_e32 v76, v76
	v_exp_f32_e32 v77, v77
	s_waitcnt vmcnt(2)
	v_lshlrev_b32_e32 v208, 16, v116
	v_and_b32_e32 v209, 0xffff0000, v116
	v_pk_mul_f32 v[74:75], v[74:75], v[208:209]
	v_lshlrev_b32_e32 v210, 16, v117
	v_pk_mul_f32 v[78:79], v[68:69], v[74:75]
	v_rcp_f32_e32 v68, v76
	v_rcp_f32_e32 v69, v77
	v_and_b32_e32 v211, 0xffff0000, v117
	v_mul_f32_e32 v80, 0x3fb8aa3b, v84
	v_exp_f32_e32 v80, v80
	v_pk_mul_f32 v[82:83], v[68:69], v[210:211]
	v_mul_f32_e32 v69, 0x3fb8aa3b, v81
	v_exp_f32_e32 v81, v69
	v_mul_f32_e32 v69, 0x3fb8aa3b, v86
	v_pk_mul_f32 v[84:85], v[70:71], v[82:83]
	v_exp_f32_e32 v70, v69
	v_mul_f32_e32 v69, 0x3fb8aa3b, v87
	v_exp_f32_e32 v71, v69
	v_rcp_f32_e32 v68, v80
	v_rcp_f32_e32 v69, v81
	v_rcp_f32_e32 v86, v70
	v_rcp_f32_e32 v87, v71
	v_lshlrev_b32_e32 v88, 16, v112
	v_and_b32_e32 v89, 0xffff0000, v112
	v_lshlrev_b32_e32 v90, 16, v113
	v_and_b32_e32 v91, 0xffff0000, v113
	v_lshlrev_b32_e32 v92, 16, v114
	v_and_b32_e32 v93, 0xffff0000, v114
	v_lshlrev_b32_e32 v94, 16, v115
	v_and_b32_e32 v95, 0xffff0000, v115
	v_lshlrev_b32_e32 v212, 16, v118
	v_and_b32_e32 v213, 0xffff0000, v118
	v_lshlrev_b32_e32 v214, 16, v119
	v_and_b32_e32 v215, 0xffff0000, v119
	v_pk_mul_f32 v[72:73], v[72:73], v[88:89]
	v_pk_mul_f32 v[76:77], v[76:77], v[90:91]
	v_pk_mul_f32 v[80:81], v[80:81], v[92:93]
	v_pk_mul_f32 v[88:89], v[68:69], v[212:213]
	v_pk_mul_f32 v[68:69], v[70:71], v[94:95]
	v_pk_mul_f32 v[86:87], v[86:87], v[214:215]
	v_pk_mul_f32 v[90:91], v[64:65], v[88:89]
	v_pk_mul_f32 v[92:93], v[66:67], v[86:87]
	v_cvt_pk_bf16_f32 v64, v72, v73
	v_cvt_pk_bf16_f32 v65, v76, v77
	v_cvt_pk_bf16_f32 v66, v80, v81
	v_cvt_pk_bf16_f32 v67, v68, v69
	v_cvt_pk_bf16_f32 v68, v74, v75
	v_cvt_pk_bf16_f32 v69, v82, v83
	v_cvt_pk_bf16_f32 v70, v88, v89
	v_cvt_pk_bf16_f32 v71, v86, v87
	ds_write_b128 v180, v[64:67]
	ds_write_b128 v180, v[68:71] offset:17408
	v_cvt_pk_bf16_f32 v64, v78, v79
	ds_write_b16 v181, v64 offset:34816
	ds_write_b16_d16_hi v181, v64 offset:34960
	v_cvt_pk_bf16_f32 v64, v84, v85
	ds_write_b16 v181, v64 offset:35104
	ds_write_b16_d16_hi v181, v64 offset:35248
	v_cvt_pk_bf16_f32 v64, v90, v91
	ds_write_b16 v181, v64 offset:35392
	ds_write_b16_d16_hi v181, v64 offset:35536
	v_cvt_pk_bf16_f32 v64, v92, v93
	ds_write_b16 v181, v64 offset:35680
	ds_write_b16_d16_hi v181, v64 offset:35824
	s_waitcnt vmcnt(2)
	ds_write_b16 v181, v120 offset:53248
	ds_write_b16_d16_hi v181, v120 offset:53392
	ds_write_b16 v181, v121 offset:53536
	ds_write_b16_d16_hi v181, v121 offset:53680
	ds_write_b16 v181, v122 offset:53824
	ds_write_b16_d16_hi v181, v122 offset:53968
	ds_write_b16 v181, v123 offset:54112
	ds_write_b16_d16_hi v181, v123 offset:54256
	s_and_saveexec_b64 s[0:1], s[4:5]
	ds_write_b128 v203, v[124:127]
	s_or_b64 exec, exec, s[0:1]
	s_cmpk_lt_u32 s95, 0x42
	s_cselect_b64 s[0:1], -1, 0
	s_and_b64 s[50:51], s[4:5], s[0:1]
	s_and_saveexec_b64 s[0:1], s[50:51]
	s_cbranch_execz .LBB0_2563
	s_cmp_lt_u32 s95, 2
	s_movk_i32 s50, 0xff80
	s_cselect_b32 s50, 0x80, s50
	s_cselect_b32 s51, 0xff, s94
	s_cselect_b32 s84, s93, s87
	s_add_i32 s85, s86, s50
	s_sub_i32 s50, s51, s50
	v_add_u32_e32 v64, s85, v153
	v_add_u32_e32 v65, s50, v96
	v_cndmask_b32_e64 v64, v65, v64, s[82:83]
	v_add_u32_e32 v64, s84, v64
	v_ashrrev_i32_e32 v65, 31, v64
	v_lshlrev_b64 v[64:65], 6, v[64:65]
	v_lshl_add_u64 v[64:65], v[98:99], 0, v[64:65]
	global_load_dwordx4 v[124:127], v[64:65], off
